# code placement: every GEMM K-loop head placed at 4 mod 8 bytes (.p2align 3 + one s_nop in front of the loop label)
# baseline (speedup 1.0000x reference)
; template <class Epi, class Sched, bool ALIGN_EPI = false, bool SP2 = false>
; __device__ __forceinline__ void gemm_phase(PG8_LAS unsigned char* lds, const Gemm g, const Sched& S, const Epi& E, const int tid) {
;     ...
;         const bool has_next = S.next(ui + 1, nxt);
;         const char* nA = has_next ? (const char*)g.A + (size_t)nxt.pm * tstepA : cA; const char* nB = has_next ? (const char*)g.Bt + (size_t)nxt.pn * tstep : cB;
;         for (int t = 0; t < nt; t += 2) {
;     ...
; #pragma unroll
;         for (int a = 0; a < 2; ++a)
; #pragma unroll
;             for (int b = 0; b < 2; ++b)
; #pragma unroll
;                 for (int m = 0; m < 4; ++m)
; #pragma unroll
;                     for (int n = 0; n < 2; ++n) acc[a][b][m][n] = (f32x4){0.f, 0.f, 0.f, 0.f};
.LBB0_278:
	s_ashr_i32 s17, s16, 31
	s_lshl_b64 s[18:19], s[16:17], 19
	s_add_u32 s18, s1, s18
	s_addc_u32 s19, s30, s19
	s_and_b64 s[20:21], s[2:3], exec
	s_cselect_b32 s17, s19, s25
	s_cselect_b32 s54, s18, s24
	s_ashr_i32 s15, s14, 31
	s_lshl_b64 s[20:21], s[14:15], 19
	s_add_u32 s20, s31, s20
	s_addc_u32 s21, s33, s21
	s_and_b64 s[28:29], s[2:3], exec
	s_cselect_b32 s15, s21, s27
	s_cselect_b32 s55, s20, s26
	s_add_u32 s24, s24, 0x40080
	s_addc_u32 s25, s25, 0
	s_add_u32 s56, s26, 0x100
	v_mov_b64_e32 v[0:1], 0
	v_mov_b64_e32 v[2:3], 0
	v_mov_b64_e32 v[4:5], 0
	v_mov_b64_e32 v[6:7], 0
	v_mov_b64_e32 v[8:9], 0
	v_mov_b64_e32 v[10:11], 0
	v_mov_b64_e32 v[12:13], 0
	v_mov_b64_e32 v[14:15], 0
	v_mov_b64_e32 v[16:17], 0
	v_mov_b64_e32 v[18:19], 0
	v_mov_b64_e32 v[20:21], 0
	v_mov_b64_e32 v[22:23], 0
	v_mov_b64_e32 v[24:25], 0
	v_mov_b64_e32 v[26:27], 0
	v_mov_b64_e32 v[28:29], 0
	v_mov_b64_e32 v[30:31], 0
	v_mov_b64_e32 v[32:33], 0
	v_mov_b64_e32 v[34:35], 0
	v_mov_b64_e32 v[36:37], 0
	v_mov_b64_e32 v[38:39], 0
	v_mov_b64_e32 v[40:41], 0
	v_mov_b64_e32 v[42:43], 0
	v_mov_b64_e32 v[44:45], 0
	v_mov_b64_e32 v[46:47], 0
	v_mov_b64_e32 v[48:49], 0
	v_mov_b64_e32 v[50:51], 0
	v_mov_b64_e32 v[52:53], 0
	v_mov_b64_e32 v[54:55], 0
	v_mov_b64_e32 v[56:57], 0
	v_mov_b64_e32 v[58:59], 0
	v_mov_b64_e32 v[60:61], 0
	v_mov_b64_e32 v[62:63], 0
	v_mov_b64_e32 v[64:65], 0
	v_mov_b64_e32 v[66:67], 0
	v_mov_b64_e32 v[68:69], 0
	v_mov_b64_e32 v[70:71], 0
	v_mov_b64_e32 v[72:73], 0
	v_mov_b64_e32 v[74:75], 0
	v_mov_b64_e32 v[76:77], 0
	v_mov_b64_e32 v[78:79], 0
	v_mov_b64_e32 v[80:81], 0
	v_mov_b64_e32 v[82:83], 0
	v_mov_b64_e32 v[84:85], 0
	v_mov_b64_e32 v[86:87], 0
	v_mov_b64_e32 v[88:89], 0
	v_mov_b64_e32 v[90:91], 0
	v_mov_b64_e32 v[92:93], 0
	v_mov_b64_e32 v[94:95], 0
	v_mov_b64_e32 v[96:97], 0
	v_mov_b64_e32 v[98:99], 0
	v_mov_b64_e32 v[100:101], 0
	v_mov_b64_e32 v[102:103], 0
	v_mov_b64_e32 v[104:105], 0
	v_mov_b64_e32 v[106:107], 0
	v_mov_b64_e32 v[108:109], 0
	v_mov_b64_e32 v[110:111], 0
	v_mov_b64_e32 v[112:113], 0
	v_mov_b64_e32 v[114:115], 0
	v_mov_b64_e32 v[116:117], 0
	v_mov_b64_e32 v[118:119], 0
	v_mov_b64_e32 v[120:121], 0
	v_mov_b64_e32 v[122:123], 0
	v_mov_b64_e32 v[124:125], 0
	v_mov_b64_e32 v[126:127], 0
	s_addc_u32 s57, s27, 0
	s_mov_b32 s58, -2
	.p2align	3
	s_nop 0

; template <class Epi, class Sched, bool ALIGN_EPI = false, bool SP2 = false>
; __device__ __forceinline__ void gemm_phase(PG8_LAS unsigned char* lds, const Gemm g, const Sched& S, const Epi& E, const int tid) {
;     ...
; #pragma unroll
;         for (int a = 0; a < 2; ++a)
; #pragma unroll
;             for (int b = 0; b < 2; ++b)
; #pragma unroll
;                 for (int m = 0; m < 4; ++m)
; #pragma unroll
;                     for (int n = 0; n < 2; ++n) acc[a][b][m][n] = (f32x4){0.f, 0.f, 0.f, 0.f};
.LBB0_352:
	s_add_u32 s57, s24, 0x100
	v_mov_b64_e32 v[0:1], 0
	v_mov_b64_e32 v[2:3], 0
	v_mov_b64_e32 v[4:5], 0
	v_mov_b64_e32 v[6:7], 0
	v_mov_b64_e32 v[8:9], 0
	v_mov_b64_e32 v[10:11], 0
	v_mov_b64_e32 v[12:13], 0
	v_mov_b64_e32 v[14:15], 0
	v_mov_b64_e32 v[16:17], 0
	v_mov_b64_e32 v[18:19], 0
	v_mov_b64_e32 v[20:21], 0
	v_mov_b64_e32 v[22:23], 0
	v_mov_b64_e32 v[24:25], 0
	v_mov_b64_e32 v[26:27], 0
	v_mov_b64_e32 v[28:29], 0
	v_mov_b64_e32 v[30:31], 0
	v_mov_b64_e32 v[32:33], 0
	v_mov_b64_e32 v[34:35], 0
	v_mov_b64_e32 v[36:37], 0
	v_mov_b64_e32 v[38:39], 0
	v_mov_b64_e32 v[40:41], 0
	v_mov_b64_e32 v[42:43], 0
	v_mov_b64_e32 v[44:45], 0
	v_mov_b64_e32 v[46:47], 0
	v_mov_b64_e32 v[48:49], 0
	v_mov_b64_e32 v[50:51], 0
	v_mov_b64_e32 v[52:53], 0
	v_mov_b64_e32 v[54:55], 0
	v_mov_b64_e32 v[56:57], 0
	v_mov_b64_e32 v[58:59], 0
	v_mov_b64_e32 v[60:61], 0
	v_mov_b64_e32 v[62:63], 0
	v_mov_b64_e32 v[64:65], 0
	v_mov_b64_e32 v[66:67], 0
	v_mov_b64_e32 v[68:69], 0
	v_mov_b64_e32 v[70:71], 0
	v_mov_b64_e32 v[72:73], 0
	v_mov_b64_e32 v[74:75], 0
	v_mov_b64_e32 v[76:77], 0
	v_mov_b64_e32 v[78:79], 0
	v_mov_b64_e32 v[80:81], 0
	v_mov_b64_e32 v[82:83], 0
	v_mov_b64_e32 v[84:85], 0
	v_mov_b64_e32 v[86:87], 0
	v_mov_b64_e32 v[88:89], 0
	v_mov_b64_e32 v[90:91], 0
	v_mov_b64_e32 v[92:93], 0
	v_mov_b64_e32 v[94:95], 0
	v_mov_b64_e32 v[96:97], 0
	v_mov_b64_e32 v[98:99], 0
	v_mov_b64_e32 v[100:101], 0
	v_mov_b64_e32 v[102:103], 0
	v_mov_b64_e32 v[104:105], 0
	v_mov_b64_e32 v[106:107], 0
	v_mov_b64_e32 v[108:109], 0
	v_mov_b64_e32 v[110:111], 0
	v_mov_b64_e32 v[112:113], 0
	v_mov_b64_e32 v[114:115], 0
	v_mov_b64_e32 v[116:117], 0
	v_mov_b64_e32 v[118:119], 0
	v_mov_b64_e32 v[120:121], 0
	v_mov_b64_e32 v[122:123], 0
	v_mov_b64_e32 v[124:125], 0
	v_mov_b64_e32 v[126:127], 0
	s_addc_u32 s58, s25, 0
	s_mov_b32 s59, -2
	s_waitcnt lgkmcnt(0)
	.p2align	3
	s_nop 0

; template <class Epi, class Sched, bool ALIGN_EPI = false, bool SP2 = false>
; __device__ __forceinline__ void gemm_phase(PG8_LAS unsigned char* lds, const Gemm g, const Sched& S, const Epi& E, const int tid) {
;     ...
;         const bool has_next = S.next(ui + 1, nxt);
;         const char* nA = has_next ? (const char*)g.A + (size_t)nxt.pm * tstepA : cA; const char* nB = has_next ? (const char*)g.Bt + (size_t)nxt.pn * tstep : cB;
;         for (int t = 0; t < nt; t += 2) {
;     ...
; #pragma unroll
;         for (int a = 0; a < 2; ++a)
; #pragma unroll
;             for (int b = 0; b < 2; ++b)
; #pragma unroll
;                 for (int m = 0; m < 4; ++m)
; #pragma unroll
;                     for (int n = 0; n < 2; ++n) acc[a][b][m][n] = (f32x4){0.f, 0.f, 0.f, 0.f};
.LBB0_436:
	s_ashr_i32 s25, s24, 31
	s_lshl_b64 s[26:27], s[24:25], 19
	s_add_u32 s26, s41, s26
	s_addc_u32 s27, s42, s27
	s_and_b64 s[28:29], s[2:3], exec
	s_cselect_b32 s0, s27, s31
	s_cselect_b32 s21, s26, s30
	s_ashr_i32 s23, s22, 31
	s_lshl_b64 s[28:29], s[22:23], 19
	s_add_u32 s28, s43, s28
	s_addc_u32 s29, s50, s29
	s_and_b64 s[36:37], s[2:3], exec
	s_cselect_b32 s23, s29, s35
	s_cselect_b32 s25, s28, s34
	s_add_u32 s30, s30, 0x40080
	s_addc_u32 s31, s31, 0
	s_add_u32 s33, s34, 0x100
	v_mov_b64_e32 v[0:1], 0
	v_mov_b64_e32 v[2:3], 0
	v_mov_b64_e32 v[4:5], 0
	v_mov_b64_e32 v[6:7], 0
	v_mov_b64_e32 v[8:9], 0
	v_mov_b64_e32 v[10:11], 0
	v_mov_b64_e32 v[12:13], 0
	v_mov_b64_e32 v[14:15], 0
	v_mov_b64_e32 v[16:17], 0
	v_mov_b64_e32 v[18:19], 0
	v_mov_b64_e32 v[20:21], 0
	v_mov_b64_e32 v[22:23], 0
	v_mov_b64_e32 v[24:25], 0
	v_mov_b64_e32 v[26:27], 0
	v_mov_b64_e32 v[28:29], 0
	v_mov_b64_e32 v[30:31], 0
	v_mov_b64_e32 v[32:33], 0
	v_mov_b64_e32 v[34:35], 0
	v_mov_b64_e32 v[36:37], 0
	v_mov_b64_e32 v[38:39], 0
	v_mov_b64_e32 v[40:41], 0
	v_mov_b64_e32 v[42:43], 0
	v_mov_b64_e32 v[44:45], 0
	v_mov_b64_e32 v[46:47], 0
	v_mov_b64_e32 v[48:49], 0
	v_mov_b64_e32 v[50:51], 0
	v_mov_b64_e32 v[52:53], 0
	v_mov_b64_e32 v[54:55], 0
	v_mov_b64_e32 v[56:57], 0
	v_mov_b64_e32 v[58:59], 0
	v_mov_b64_e32 v[60:61], 0
	v_mov_b64_e32 v[62:63], 0
	v_mov_b64_e32 v[64:65], 0
	v_mov_b64_e32 v[66:67], 0
	v_mov_b64_e32 v[68:69], 0
	v_mov_b64_e32 v[70:71], 0
	v_mov_b64_e32 v[72:73], 0
	v_mov_b64_e32 v[74:75], 0
	v_mov_b64_e32 v[76:77], 0
	v_mov_b64_e32 v[78:79], 0
	v_mov_b64_e32 v[80:81], 0
	v_mov_b64_e32 v[82:83], 0
	v_mov_b64_e32 v[84:85], 0
	v_mov_b64_e32 v[86:87], 0
	v_mov_b64_e32 v[88:89], 0
	v_mov_b64_e32 v[90:91], 0
	v_mov_b64_e32 v[92:93], 0
	v_mov_b64_e32 v[94:95], 0
	v_mov_b64_e32 v[96:97], 0
	v_mov_b64_e32 v[98:99], 0
	v_mov_b64_e32 v[100:101], 0
	v_mov_b64_e32 v[102:103], 0
	v_mov_b64_e32 v[104:105], 0
	v_mov_b64_e32 v[106:107], 0
	v_mov_b64_e32 v[108:109], 0
	v_mov_b64_e32 v[110:111], 0
	v_mov_b64_e32 v[112:113], 0
	v_mov_b64_e32 v[114:115], 0
	v_mov_b64_e32 v[116:117], 0
	v_mov_b64_e32 v[118:119], 0
	v_mov_b64_e32 v[120:121], 0
	v_mov_b64_e32 v[122:123], 0
	v_mov_b64_e32 v[124:125], 0
	v_mov_b64_e32 v[126:127], 0
	s_addc_u32 s38, s35, 0
	s_mov_b32 s39, -2
	.p2align	3
	s_nop 0

; template <class Epi, class Sched, bool ALIGN_EPI = false, bool SP2 = false>
; __device__ __forceinline__ void gemm_phase(PG8_LAS unsigned char* lds, const Gemm g, const Sched& S, const Epi& E, const int tid) {
;     ...
;         const bool has_next = S.next(ui + 1, nxt);
;         const char* nA = has_next ? (const char*)g.A + (size_t)nxt.pm * tstepA : cA; const char* nB = has_next ? (const char*)g.Bt + (size_t)nxt.pn * tstep : cB;
;         for (int t = 0; t < nt; t += 2) {
;     ...
; #pragma unroll
;         for (int a = 0; a < 2; ++a)
; #pragma unroll
;             for (int b = 0; b < 2; ++b)
; #pragma unroll
;                 for (int m = 0; m < 4; ++m)
; #pragma unroll
;                     for (int n = 0; n < 2; ++n) acc[a][b][m][n] = (f32x4){0.f, 0.f, 0.f, 0.f};
.LBB0_764:
	s_ashr_i32 s21, s20, 31
	s_lshl_b64 s[24:25], s[20:21], 19
	s_add_u32 s24, s36, s24
	s_addc_u32 s25, s37, s25
	s_and_b64 s[6:7], s[6:7], exec
	s_cselect_b32 s21, s25, s31
	s_cselect_b32 s58, s24, s30
	s_add_u32 s59, s30, 0x100
	v_mov_b64_e32 v[0:1], 0
	v_mov_b64_e32 v[2:3], 0
	v_mov_b64_e32 v[4:5], 0
	v_mov_b64_e32 v[6:7], 0
	v_mov_b64_e32 v[8:9], 0
	v_mov_b64_e32 v[10:11], 0
	v_mov_b64_e32 v[12:13], 0
	v_mov_b64_e32 v[14:15], 0
	v_mov_b64_e32 v[16:17], 0
	v_mov_b64_e32 v[18:19], 0
	v_mov_b64_e32 v[20:21], 0
	v_mov_b64_e32 v[22:23], 0
	v_mov_b64_e32 v[24:25], 0
	v_mov_b64_e32 v[26:27], 0
	v_mov_b64_e32 v[28:29], 0
	v_mov_b64_e32 v[30:31], 0
	v_mov_b64_e32 v[32:33], 0
	v_mov_b64_e32 v[34:35], 0
	v_mov_b64_e32 v[36:37], 0
	v_mov_b64_e32 v[38:39], 0
	v_mov_b64_e32 v[40:41], 0
	v_mov_b64_e32 v[42:43], 0
	v_mov_b64_e32 v[44:45], 0
	v_mov_b64_e32 v[46:47], 0
	v_mov_b64_e32 v[48:49], 0
	v_mov_b64_e32 v[50:51], 0
	v_mov_b64_e32 v[52:53], 0
	v_mov_b64_e32 v[54:55], 0
	v_mov_b64_e32 v[56:57], 0
	v_mov_b64_e32 v[58:59], 0
	v_mov_b64_e32 v[60:61], 0
	v_mov_b64_e32 v[62:63], 0
	v_mov_b64_e32 v[64:65], 0
	v_mov_b64_e32 v[66:67], 0
	v_mov_b64_e32 v[68:69], 0
	v_mov_b64_e32 v[70:71], 0
	v_mov_b64_e32 v[72:73], 0
	v_mov_b64_e32 v[74:75], 0
	v_mov_b64_e32 v[76:77], 0
	v_mov_b64_e32 v[78:79], 0
	v_mov_b64_e32 v[80:81], 0
	v_mov_b64_e32 v[82:83], 0
	v_mov_b64_e32 v[84:85], 0
	v_mov_b64_e32 v[86:87], 0
	v_mov_b64_e32 v[88:89], 0
	v_mov_b64_e32 v[90:91], 0
	v_mov_b64_e32 v[92:93], 0
	v_mov_b64_e32 v[94:95], 0
	v_mov_b64_e32 v[96:97], 0
	v_mov_b64_e32 v[98:99], 0
	v_mov_b64_e32 v[100:101], 0
	v_mov_b64_e32 v[102:103], 0
	v_mov_b64_e32 v[104:105], 0
	v_mov_b64_e32 v[106:107], 0
	v_mov_b64_e32 v[108:109], 0
	v_mov_b64_e32 v[110:111], 0
	v_mov_b64_e32 v[112:113], 0
	v_mov_b64_e32 v[114:115], 0
	v_mov_b64_e32 v[116:117], 0
	v_mov_b64_e32 v[118:119], 0
	v_mov_b64_e32 v[120:121], 0
	v_mov_b64_e32 v[122:123], 0
	v_mov_b64_e32 v[124:125], 0
	v_mov_b64_e32 v[126:127], 0
	s_addc_u32 s60, s31, 0
	s_mov_b32 s61, -2
	s_waitcnt lgkmcnt(0)
	.p2align	3
	s_nop 0

; template <class Epi, class Sched, bool ALIGN_EPI = false, bool SP2 = false>
; __device__ __forceinline__ void gemm_phase(PG8_LAS unsigned char* lds, const Gemm g, const Sched& S, const Epi& E, const int tid) {
;     ...
; #pragma unroll
;         for (int a = 0; a < 2; ++a)
; #pragma unroll
;             for (int b = 0; b < 2; ++b)
; #pragma unroll
;                 for (int m = 0; m < 4; ++m)
; #pragma unroll
;                     for (int n = 0; n < 2; ++n) acc[a][b][m][n] = (f32x4){0.f, 0.f, 0.f, 0.f};
.LBB0_922:
	s_add_u32 s61, s28, 0x100
	v_mov_b64_e32 v[0:1], 0
	v_mov_b64_e32 v[2:3], 0
	v_mov_b64_e32 v[4:5], 0
	v_mov_b64_e32 v[6:7], 0
	v_mov_b64_e32 v[8:9], 0
	v_mov_b64_e32 v[10:11], 0
	v_mov_b64_e32 v[12:13], 0
	v_mov_b64_e32 v[14:15], 0
	v_mov_b64_e32 v[16:17], 0
	v_mov_b64_e32 v[18:19], 0
	v_mov_b64_e32 v[20:21], 0
	v_mov_b64_e32 v[22:23], 0
	v_mov_b64_e32 v[24:25], 0
	v_mov_b64_e32 v[26:27], 0
	v_mov_b64_e32 v[28:29], 0
	v_mov_b64_e32 v[30:31], 0
	v_mov_b64_e32 v[32:33], 0
	v_mov_b64_e32 v[34:35], 0
	v_mov_b64_e32 v[36:37], 0
	v_mov_b64_e32 v[38:39], 0
	v_mov_b64_e32 v[40:41], 0
	v_mov_b64_e32 v[42:43], 0
	v_mov_b64_e32 v[44:45], 0
	v_mov_b64_e32 v[46:47], 0
	v_mov_b64_e32 v[48:49], 0
	v_mov_b64_e32 v[50:51], 0
	v_mov_b64_e32 v[52:53], 0
	v_mov_b64_e32 v[54:55], 0
	v_mov_b64_e32 v[56:57], 0
	v_mov_b64_e32 v[58:59], 0
	v_mov_b64_e32 v[60:61], 0
	v_mov_b64_e32 v[62:63], 0
	v_mov_b64_e32 v[64:65], 0
	v_mov_b64_e32 v[66:67], 0
	v_mov_b64_e32 v[68:69], 0
	v_mov_b64_e32 v[70:71], 0
	v_mov_b64_e32 v[72:73], 0
	v_mov_b64_e32 v[74:75], 0
	v_mov_b64_e32 v[76:77], 0
	v_mov_b64_e32 v[78:79], 0
	v_mov_b64_e32 v[80:81], 0
	v_mov_b64_e32 v[82:83], 0
	v_mov_b64_e32 v[84:85], 0
	v_mov_b64_e32 v[86:87], 0
	v_mov_b64_e32 v[88:89], 0
	v_mov_b64_e32 v[90:91], 0
	v_mov_b64_e32 v[92:93], 0
	v_mov_b64_e32 v[94:95], 0
	v_mov_b64_e32 v[96:97], 0
	v_mov_b64_e32 v[98:99], 0
	v_mov_b64_e32 v[100:101], 0
	v_mov_b64_e32 v[102:103], 0
	v_mov_b64_e32 v[104:105], 0
	v_mov_b64_e32 v[106:107], 0
	v_mov_b64_e32 v[108:109], 0
	v_mov_b64_e32 v[110:111], 0
	v_mov_b64_e32 v[112:113], 0
	v_mov_b64_e32 v[114:115], 0
	v_mov_b64_e32 v[116:117], 0
	v_mov_b64_e32 v[118:119], 0
	v_mov_b64_e32 v[120:121], 0
	v_mov_b64_e32 v[122:123], 0
	v_mov_b64_e32 v[124:125], 0
	v_mov_b64_e32 v[126:127], 0
	s_addc_u32 s62, s29, 0
	s_mov_b32 s63, -2
	s_waitcnt lgkmcnt(0)
	.p2align	3
	s_nop 0

; template <class Epi, class Sched, bool ALIGN_EPI = false, bool SP2 = false>
; __device__ __forceinline__ void gemm_phase(PG8_LAS unsigned char* lds, const Gemm g, const Sched& S, const Epi& E, const int tid) {
;     ...
;         const bool has_next = S.next(ui + 1, nxt);
;         const char* nA = has_next ? (const char*)g.A + (size_t)nxt.pm * tstepA : cA; const char* nB = has_next ? (const char*)g.Bt + (size_t)nxt.pn * tstep : cB;
;         for (int t = 0; t < nt; t += 2) {
;     ...
; #pragma unroll
;         for (int a = 0; a < 2; ++a)
; #pragma unroll
;             for (int b = 0; b < 2; ++b)
; #pragma unroll
;                 for (int m = 0; m < 4; ++m)
; #pragma unroll
;                     for (int n = 0; n < 2; ++n) acc[a][b][m][n] = (f32x4){0.f, 0.f, 0.f, 0.f};
.LBB0_1006:
	s_ashr_i32 s19, s18, 31
	s_lshl_b64 s[20:21], s[18:19], 19
	s_add_u32 s20, s1, s20
	s_addc_u32 s21, s33, s21
	s_and_b64 s[22:23], s[2:3], exec
	s_cselect_b32 s19, s21, s27
	s_cselect_b32 s56, s20, s26
	s_ashr_i32 s17, s16, 31
	s_lshl_b64 s[22:23], s[16:17], 19
	s_add_u32 s22, s34, s22
	s_addc_u32 s23, s35, s23
	s_and_b64 s[30:31], s[2:3], exec
	s_cselect_b32 s17, s23, s29
	s_cselect_b32 s57, s22, s28
	s_add_u32 s26, s26, 0x40080
	s_addc_u32 s27, s27, 0
	s_add_u32 s58, s28, 0x100
	v_mov_b64_e32 v[0:1], 0
	v_mov_b64_e32 v[2:3], 0
	v_mov_b64_e32 v[4:5], 0
	v_mov_b64_e32 v[6:7], 0
	v_mov_b64_e32 v[8:9], 0
	v_mov_b64_e32 v[10:11], 0
	v_mov_b64_e32 v[12:13], 0
	v_mov_b64_e32 v[14:15], 0
	v_mov_b64_e32 v[16:17], 0
	v_mov_b64_e32 v[18:19], 0
	v_mov_b64_e32 v[20:21], 0
	v_mov_b64_e32 v[22:23], 0
	v_mov_b64_e32 v[24:25], 0
	v_mov_b64_e32 v[26:27], 0
	v_mov_b64_e32 v[28:29], 0
	v_mov_b64_e32 v[30:31], 0
	v_mov_b64_e32 v[32:33], 0
	v_mov_b64_e32 v[34:35], 0
	v_mov_b64_e32 v[36:37], 0
	v_mov_b64_e32 v[38:39], 0
	v_mov_b64_e32 v[40:41], 0
	v_mov_b64_e32 v[42:43], 0
	v_mov_b64_e32 v[44:45], 0
	v_mov_b64_e32 v[46:47], 0
	v_mov_b64_e32 v[48:49], 0
	v_mov_b64_e32 v[50:51], 0
	v_mov_b64_e32 v[52:53], 0
	v_mov_b64_e32 v[54:55], 0
	v_mov_b64_e32 v[56:57], 0
	v_mov_b64_e32 v[58:59], 0
	v_mov_b64_e32 v[60:61], 0
	v_mov_b64_e32 v[62:63], 0
	v_mov_b64_e32 v[64:65], 0
	v_mov_b64_e32 v[66:67], 0
	v_mov_b64_e32 v[68:69], 0
	v_mov_b64_e32 v[70:71], 0
	v_mov_b64_e32 v[72:73], 0
	v_mov_b64_e32 v[74:75], 0
	v_mov_b64_e32 v[76:77], 0
	v_mov_b64_e32 v[78:79], 0
	v_mov_b64_e32 v[80:81], 0
	v_mov_b64_e32 v[82:83], 0
	v_mov_b64_e32 v[84:85], 0
	v_mov_b64_e32 v[86:87], 0
	v_mov_b64_e32 v[88:89], 0
	v_mov_b64_e32 v[90:91], 0
	v_mov_b64_e32 v[92:93], 0
	v_mov_b64_e32 v[94:95], 0
	v_mov_b64_e32 v[96:97], 0
	v_mov_b64_e32 v[98:99], 0
	v_mov_b64_e32 v[100:101], 0
	v_mov_b64_e32 v[102:103], 0
	v_mov_b64_e32 v[104:105], 0
	v_mov_b64_e32 v[106:107], 0
	v_mov_b64_e32 v[108:109], 0
	v_mov_b64_e32 v[110:111], 0
	v_mov_b64_e32 v[112:113], 0
	v_mov_b64_e32 v[114:115], 0
	v_mov_b64_e32 v[116:117], 0
	v_mov_b64_e32 v[118:119], 0
	v_mov_b64_e32 v[120:121], 0
	v_mov_b64_e32 v[122:123], 0
	v_mov_b64_e32 v[124:125], 0
	v_mov_b64_e32 v[126:127], 0
	s_addc_u32 s59, s29, 0
	s_mov_b32 s60, -2
	.p2align	3
	s_nop 0

; template <class Epi, class Sched, bool ALIGN_EPI = false, bool SP2 = false>
; __device__ __forceinline__ void gemm_phase(PG8_LAS unsigned char* lds, const Gemm g, const Sched& S, const Epi& E, const int tid) {
;     ...
; #pragma unroll
;         for (int a = 0; a < 2; ++a)
; #pragma unroll
;             for (int b = 0; b < 2; ++b)
; #pragma unroll
;                 for (int m = 0; m < 4; ++m)
; #pragma unroll
;                     for (int n = 0; n < 2; ++n) acc[a][b][m][n] = (f32x4){0.f, 0.f, 0.f, 0.f};
.LBB0_1080:
	s_add_u32 s61, s28, 0x100
	v_mov_b32_e32 v0, 0
	s_addc_u32 s62, s29, 0
	s_mov_b32 s63, -2
	s_waitcnt lgkmcnt(0)
	v_mov_b32_e32 v1, v0
	v_mov_b32_e32 v2, v0
	v_mov_b32_e32 v3, v0
	v_mov_b32_e32 v4, v0
	v_mov_b32_e32 v5, v0
	v_mov_b32_e32 v6, v0
	v_mov_b32_e32 v7, v0
	v_mov_b32_e32 v16, v0
	v_mov_b32_e32 v17, v0
	v_mov_b32_e32 v18, v0
	v_mov_b32_e32 v19, v0
	v_mov_b32_e32 v20, v0
	v_mov_b32_e32 v21, v0
	v_mov_b32_e32 v22, v0
	v_mov_b32_e32 v23, v0
	v_mov_b32_e32 v32, v0
	v_mov_b32_e32 v33, v0
	v_mov_b32_e32 v34, v0
	v_mov_b32_e32 v35, v0
	v_mov_b32_e32 v36, v0
	v_mov_b32_e32 v37, v0
	v_mov_b32_e32 v38, v0
	v_mov_b32_e32 v39, v0
	v_mov_b32_e32 v48, v0
	v_mov_b32_e32 v49, v0
	v_mov_b32_e32 v50, v0
	v_mov_b32_e32 v51, v0
	v_mov_b32_e32 v52, v0
	v_mov_b32_e32 v53, v0
	v_mov_b32_e32 v54, v0
	v_mov_b32_e32 v55, v0
	v_mov_b32_e32 v8, v0
	v_mov_b32_e32 v9, v0
	v_mov_b32_e32 v10, v0
	v_mov_b32_e32 v11, v0
	v_mov_b32_e32 v12, v0
	v_mov_b32_e32 v13, v0
	v_mov_b32_e32 v14, v0
	v_mov_b32_e32 v15, v0
	v_mov_b32_e32 v24, v0
	v_mov_b32_e32 v25, v0
	v_mov_b32_e32 v26, v0
	v_mov_b32_e32 v27, v0
	v_mov_b32_e32 v28, v0
	v_mov_b32_e32 v29, v0
	v_mov_b32_e32 v30, v0
	v_mov_b32_e32 v31, v0
	v_mov_b32_e32 v40, v0
	v_mov_b32_e32 v41, v0
	v_mov_b32_e32 v42, v0
	v_mov_b32_e32 v43, v0
	v_mov_b32_e32 v44, v0
	v_mov_b32_e32 v45, v0
	v_mov_b32_e32 v46, v0
	v_mov_b32_e32 v47, v0
	v_mov_b32_e32 v56, v0
	v_mov_b32_e32 v57, v0
	v_mov_b32_e32 v58, v0
	v_mov_b32_e32 v59, v0
	v_mov_b32_e32 v60, v0
	v_mov_b32_e32 v61, v0
	v_mov_b32_e32 v62, v0
	v_mov_b32_e32 v63, v0
	v_mov_b32_e32 v64, v0
	v_mov_b32_e32 v65, v0
	v_mov_b32_e32 v66, v0
	v_mov_b32_e32 v67, v0
	v_mov_b32_e32 v68, v0
	v_mov_b32_e32 v69, v0
	v_mov_b32_e32 v70, v0
	v_mov_b32_e32 v71, v0
	v_mov_b32_e32 v96, v0
	v_mov_b32_e32 v97, v0
	v_mov_b32_e32 v98, v0
	v_mov_b32_e32 v99, v0
	v_mov_b32_e32 v100, v0
	v_mov_b32_e32 v101, v0
	v_mov_b32_e32 v102, v0
	v_mov_b32_e32 v103, v0
	v_mov_b32_e32 v112, v0
	v_mov_b32_e32 v113, v0
	v_mov_b32_e32 v114, v0
	v_mov_b32_e32 v115, v0
	v_mov_b32_e32 v116, v0
	v_mov_b32_e32 v117, v0
	v_mov_b32_e32 v118, v0
	v_mov_b32_e32 v119, v0
	v_mov_b32_e32 v128, v0
	v_mov_b32_e32 v129, v0
	v_mov_b32_e32 v130, v0
	v_mov_b32_e32 v131, v0
	v_mov_b32_e32 v132, v0
	v_mov_b32_e32 v133, v0
	v_mov_b32_e32 v134, v0
	v_mov_b32_e32 v135, v0
	v_mov_b32_e32 v72, v0
	v_mov_b32_e32 v73, v0
	v_mov_b32_e32 v74, v0
	v_mov_b32_e32 v75, v0
	v_mov_b32_e32 v76, v0
	v_mov_b32_e32 v77, v0
	v_mov_b32_e32 v78, v0
	v_mov_b32_e32 v79, v0
	v_mov_b32_e32 v104, v0
	v_mov_b32_e32 v105, v0
	v_mov_b32_e32 v106, v0
	v_mov_b32_e32 v107, v0
	v_mov_b32_e32 v108, v0
	v_mov_b32_e32 v109, v0
	v_mov_b32_e32 v110, v0
	v_mov_b32_e32 v111, v0
	v_mov_b32_e32 v120, v0
	v_mov_b32_e32 v121, v0
	v_mov_b32_e32 v122, v0
	v_mov_b32_e32 v123, v0
	v_mov_b32_e32 v124, v0
	v_mov_b32_e32 v125, v0
	v_mov_b32_e32 v126, v0
	v_mov_b32_e32 v127, v0
	v_mov_b32_e32 v136, v0
	v_mov_b32_e32 v137, v0
	v_mov_b32_e32 v138, v0
	v_mov_b32_e32 v139, v0
	v_mov_b32_e32 v140, v0
	v_mov_b32_e32 v141, v0
	v_mov_b32_e32 v142, v0
	v_mov_b32_e32 v143, v0
	.p2align	3
	s_nop 0
